# grid barrier: agent-scope invalidate kept only at the two seams where a previously loaded address can have been rewritten by another workgroup (before the q|k|gate GEMM and before attention); other se
# speedup vs baseline: 1.0292x; 1.0144x over previous
; __device__ __forceinline__ void xcd_barrier(const XcdBarrier& b) {
;     ...
;             __builtin_amdgcn_fence(__ATOMIC_ACQUIRE, "agent");
;             asm volatile("s_waitcnt vmcnt(0)" ::: "memory");
;         }
;     }
;     __syncthreads();
.Lmy_bar_go_0:
.LBB0_176:
	s_or_b64 exec, exec, s[2:3]
	s_waitcnt lgkmcnt(0)
	s_barrier

; __device__ __forceinline__ void xcd_barrier(const XcdBarrier& b) {
;     ...
;             __builtin_amdgcn_fence(__ATOMIC_ACQUIRE, "agent");
;             asm volatile("s_waitcnt vmcnt(0)" ::: "memory");
;         }
;     }
;     __syncthreads();
.Lmy_bar_go_1:
.LBB0_289:
	s_or_b64 exec, exec, s[4:5]
	s_waitcnt lgkmcnt(0)
	s_barrier
